# MLA loop re-rotated: PV of tile t-1 first (operands already in registers, covers LDS latency), row-max check before softmax, deferred accumulator rescale; dilated prefetch kept
# baseline (speedup 1.0000x reference)
; #define LAS __attribute__((address_space(3)))
; __device__ __forceinline__ void mla_unit(int h, int qb, const bf16_t* __restrict__ Qm, const bf16_t* __restrict__ Km, const bf16_t* __restrict__ Kr, const bf16_t* __restrict__ Vm, bf16_t* ZM, LAS char* lds) {
;     int tid_ = threadIdx.x; asm volatile("" : "+v"(tid_)); const int tid = tid_, lane = tid & 63, r32 = lane & 31, hi = lane >> 5; const int wid = __builtin_amdgcn_readfirstlane(tid >> 6);
;     const int q0 = qb * 256, qrow = q0 + wid * 32 + r32;
;     bf16x8 qf[6];
; #pragma unroll
;     for (int s = 0; s < 6; ++s) qf[s] = *(const bf16x8*)(Qm + (size_t)qrow * 1536 + h * 96 + 16 * s + 8 * hi);
;     const int NT = (q0 + 256) / 64;
;     const int srow = tid >> 3, sch = tid & 7, rrow = (tid & 255) >> 2, rch = tid & 3;
;     const bf16_t* kn_src = Km + (size_t)srow * 1024 + h * 64 + sch * 8;
;     const bf16_t* v_src = Vm + (size_t)srow * 1024 + h * 64 + sch * 8;
;     const bf16_t* kr_src = Kr + (size_t)rrow * 32 + rch * 8;
;     const int kn_dst = srow * KP + sch * 16, kr_dst = rrow * KP + 128 + rch * 16, v_dst = KBUF + srow * VP + sch * 16;
;     u32x4 gknA, gkrA, gvA, gknB, gkrB, gvB;
;     gknA = *(const u32x4*)kn_src; gvA = *(const u32x4*)v_src; gkrA = *(const u32x4*)kr_src;
;     *(LAS u32x4*)(lds + kn_dst) = gknA; *(LAS u32x4*)(lds + v_dst) = gvA; if (tid < 256) *(LAS u32x4*)(lds + kr_dst) = gkrA;
;     gknB = *(const u32x4*)(kn_src + (size_t)64 * 1024); gvB = *(const u32x4*)(v_src + (size_t)64 * 1024); gkrB = *(const u32x4*)(kr_src + (size_t)64 * 32);
;     __syncthreads();
;     float l = 0.f; f32x16 o0 = {}, o1 = {};
;     const int ka_off = r32 * KP + hi * 16;
;     const int i16 = lane & 15, dg = (lane >> 4) & 1;
;     const int va_off = KBUF + (4 * hi + (i16 >> 2)) * VP + (16 * dg + 4 * (i16 & 3)) * 2;
;     float mref = 0.f; f32x16 negm = {};
.LBB0_750:
	v_mov_b32_e32 v4, v196
	s_lshl_b32 s27, s26, 8
	v_readfirstlane_b32 s4, v4
	s_ashr_i32 s39, s4, 6
	s_lshl_b32 s4, s39, 5
	v_and_b32_e32 v6, 31, v4
	s_add_i32 s4, s4, s27
	v_or_b32_e32 v188, s4, v6
	v_mov_b64_e32 v[2:3], s[8:9]
	s_ashr_i32 s6, s38, 4
	v_mad_i64_i32 v[2:3], s[4:5], v188, s95, v[2:3]
	s_mul_i32 s4, s6, 0x60
	v_bfe_u32 v5, v4, 5, 1
	s_ashr_i32 s5, s4, 31
	v_lshl_add_u64 v[2:3], s[4:5], 1, v[2:3]
	v_lshlrev_b32_e32 v0, 4, v5
	v_ashrrev_i32_e32 v16, 3, v4
	v_lshl_add_u64 v[2:3], v[2:3], 0, v[0:1]
	v_ashrrev_i32_e32 v17, 31, v16
	s_lshl_b32 s24, s6, 6
	global_load_dwordx4 v[96:99], v[2:3], off
	global_load_dwordx4 v[100:103], v[2:3], off offset:32
	global_load_dwordx4 v[104:107], v[2:3], off offset:64
	global_load_dwordx4 v[108:111], v[2:3], off offset:96
	global_load_dwordx4 v[112:115], v[2:3], off offset:128
	global_load_dwordx4 v[116:119], v[2:3], off offset:160
	v_lshlrev_b64 v[8:9], 11, v[16:17]
	s_ashr_i32 s25, s24, 31
	v_lshl_add_u64 v[10:11], s[14:15], 0, v[8:9]
	s_lshl_b64 s[4:5], s[24:25], 1
	v_lshlrev_b32_e32 v2, 4, v4
	v_lshl_add_u64 v[10:11], v[10:11], 0, s[4:5]
	v_and_b32_e32 v0, 0x70, v2
	v_lshl_add_u64 v[8:9], s[18:19], 0, v[8:9]
	v_lshl_add_u64 v[190:191], v[10:11], 0, v[0:1]
	v_lshl_add_u64 v[8:9], v[8:9], 0, s[4:5]
	v_lshl_add_u64 v[192:193], v[8:9], 0, v[0:1]
	global_load_dwordx4 v[120:123], v[190:191], off
	global_load_dwordx4 v[124:127], v[192:193], off
	s_movk_i32 s4, 0xd0
	v_bfe_u32 v3, v4, 2, 6
	v_mad_u64_u32 v[18:19], s[4:5], v16, s4, v[0:1]
	v_lshlrev_b32_e32 v7, 4, v16
	v_and_b32_e32 v2, 48, v2
	v_mul_u32_u24_e32 v0, 0xd0, v3
	v_sub_u32_e32 v7, v18, v7
	v_add_u32_e32 v205, 0, v18
	v_add_u32_e32 v206, 0, v7
	v_add_u32_e32 v207, v2, v0
	v_lshlrev_b32_e32 v0, 6, v3
	v_add_u32_e32 v0, v0, v2
	v_lshl_add_u64 v[194:195], s[16:17], 0, v[0:1]
	global_load_dwordx4 v[128:131], v[194:195], off
	s_mov_b64 s[6:7], 0x20000
	v_lshl_add_u64 v[242:243], v[190:191], 0, s[6:7]
	s_mov_b64 s[6:7], 0x1000
	v_lshl_add_u64 v[244:245], v[194:195], 0, s[6:7]
	global_load_dwordx4 v[164:167], v[242:243], off
	global_load_dwordx4 v[168:171], v[244:245], off
	v_lshrrev_b32_e32 v0, 2, v4
	v_lshlrev_b32_e32 v208, 2, v5
	v_mul_u32_u24_e32 v2, 0xd0, v6
	v_lshl_add_u32 v210, v5, 4, v2
	v_and_b32_e32 v2, 16, v4
	v_and_or_b32 v0, v0, 3, v208
	v_lshlrev_b32_e32 v3, 2, v4
	v_mul_u32_u24_e32 v0, 0xc0, v0
	v_and_or_b32 v2, v3, 12, v2
	v_lshl_or_b32 v211, v2, 1, v0
	v_ashrrev_i32_e32 v189, 31, v188
	s_addk_i32 s27, 0x100
	s_lshr_b32 s40, s27, 6
	s_add_i32 s44, s40, -1
	s_add_i32 s64, s40, -4
	s_lshr_b32 s45, s39, 1
	s_add_i32 s45, s45, s40
	s_add_i32 s45, s45, -3
	s_mov_b32 s65, 0
	v_mov_b32_e32 v209, 0
	v_mov_b32_e32 v212, 0
	v_mov_b32_e32 v48, 0
	v_mov_b32_e32 v49, 0
	v_mov_b32_e32 v50, 0
	v_mov_b32_e32 v51, 0
	v_mov_b32_e32 v52, 0
	v_mov_b32_e32 v53, 0
	v_mov_b32_e32 v54, 0
	v_mov_b32_e32 v55, 0
	v_mov_b32_e32 v56, 0
	v_mov_b32_e32 v57, 0
	v_mov_b32_e32 v58, 0
	v_mov_b32_e32 v59, 0
	v_mov_b32_e32 v60, 0
	v_mov_b32_e32 v61, 0
	v_mov_b32_e32 v62, 0
	v_mov_b32_e32 v63, 0
	v_mov_b32_e32 v32, 0
	v_mov_b32_e32 v33, 0
	v_mov_b32_e32 v34, 0
	v_mov_b32_e32 v35, 0
	v_mov_b32_e32 v36, 0
	v_mov_b32_e32 v37, 0
	v_mov_b32_e32 v38, 0
	v_mov_b32_e32 v39, 0
	v_mov_b32_e32 v40, 0
	v_mov_b32_e32 v41, 0
	v_mov_b32_e32 v42, 0
	v_mov_b32_e32 v43, 0
	v_mov_b32_e32 v44, 0
	v_mov_b32_e32 v45, 0
	v_mov_b32_e32 v46, 0
	v_mov_b32_e32 v47, 0
	v_mov_b32_e32 v16, 0
	v_mov_b32_e32 v17, 0
	v_mov_b32_e32 v18, 0
	v_mov_b32_e32 v19, 0
	v_mov_b32_e32 v20, 0
	v_mov_b32_e32 v21, 0
	v_mov_b32_e32 v22, 0
	v_mov_b32_e32 v23, 0
	v_mov_b32_e32 v24, 0
	v_mov_b32_e32 v25, 0
	v_mov_b32_e32 v26, 0
	v_mov_b32_e32 v27, 0
	v_mov_b32_e32 v28, 0
	v_mov_b32_e32 v29, 0
	v_mov_b32_e32 v30, 0
	v_mov_b32_e32 v31, 0
	s_waitcnt vmcnt(0)
	ds_write_b128 v205, v[120:123] offset:0
	ds_write_b128 v206, v[124:127] offset:13312
	ds_write_b128 v207, v[128:131] offset:128
	ds_write_b128 v205, v[164:167] offset:25600
	ds_write_b128 v207, v[168:171] offset:25728
	s_waitcnt lgkmcnt(0)
	s_barrier
	s_mov_b64 s[6:7], 0x40000
	v_lshl_add_u64 v[242:243], v[190:191], 0, s[6:7]
	s_mov_b64 s[6:7], 0x20000
	v_lshl_add_u64 v[246:247], v[192:193], 0, s[6:7]
	s_mov_b64 s[6:7], 0x2000
	v_lshl_add_u64 v[244:245], v[194:195], 0, s[6:7]
	global_load_dwordx4 v[120:123], v[242:243], off
	global_load_dwordx4 v[124:127], v[246:247], off
	global_load_dwordx4 v[128:131], v[244:245], off
	ds_read_b128 v[164:167], v210 offset:0
	ds_read_b128 v[168:171], v210 offset:32
	ds_read_b128 v[172:175], v210 offset:64
	ds_read_b128 v[214:217], v210 offset:96
	s_waitcnt lgkmcnt(3)
	v_mfma_f32_32x32x16_bf16 v[64:79], v[164:167], v[96:99], v[48:63]
	ds_read_b128 v[164:167], v210 offset:128
	s_waitcnt lgkmcnt(3)
	v_mfma_f32_32x32x16_bf16 v[64:79], v[168:171], v[100:103], v[64:79]
	ds_read_b128 v[168:171], v210 offset:160
	s_waitcnt lgkmcnt(3)
	v_mfma_f32_32x32x16_bf16 v[64:79], v[172:175], v[104:107], v[64:79]
	ds_read_b128 v[172:175], v210 offset:6656
	s_waitcnt lgkmcnt(3)
	v_mfma_f32_32x32x16_bf16 v[64:79], v[214:217], v[108:111], v[64:79]
	ds_read_b128 v[214:217], v210 offset:6688
	s_waitcnt lgkmcnt(3)
	v_mfma_f32_32x32x16_bf16 v[64:79], v[164:167], v[112:115], v[64:79]
	ds_read_b128 v[164:167], v210 offset:6720
	s_waitcnt lgkmcnt(3)
	v_mfma_f32_32x32x16_bf16 v[64:79], v[168:171], v[116:119], v[64:79]
	ds_read_b128 v[168:171], v210 offset:6752
	s_waitcnt lgkmcnt(3)
	v_mfma_f32_32x32x16_bf16 v[80:95], v[172:175], v[96:99], v[48:63]
	ds_read_b128 v[172:175], v210 offset:6784
	s_waitcnt lgkmcnt(3)
	v_mfma_f32_32x32x16_bf16 v[80:95], v[214:217], v[100:103], v[80:95]
	ds_read_b128 v[214:217], v210 offset:6816
	s_waitcnt lgkmcnt(3)
	v_mfma_f32_32x32x16_bf16 v[80:95], v[164:167], v[104:107], v[80:95]
	s_waitcnt lgkmcnt(2)
	v_mfma_f32_32x32x16_bf16 v[80:95], v[168:171], v[108:111], v[80:95]
	s_waitcnt lgkmcnt(1)
	v_mfma_f32_32x32x16_bf16 v[80:95], v[172:175], v[112:115], v[80:95]
	s_waitcnt lgkmcnt(0)
	v_mfma_f32_32x32x16_bf16 v[80:95], v[214:217], v[116:119], v[80:95]
	v_mov_b32_e32 v226, 0
	v_mov_b32_e32 v227, 0
	v_mov_b32_e32 v228, 0
	v_mov_b32_e32 v229, 0
	v_mov_b32_e32 v230, 0
	v_mov_b32_e32 v231, 0
	v_mov_b32_e32 v232, 0
	v_mov_b32_e32 v233, 0
	v_mov_b32_e32 v234, 0
	v_mov_b32_e32 v235, 0
	v_mov_b32_e32 v236, 0
	v_mov_b32_e32 v237, 0
	v_mov_b32_e32 v238, 0
	v_mov_b32_e32 v239, 0
	v_mov_b32_e32 v240, 0
	v_mov_b32_e32 v241, 0
	v_mov_b32_e32 v218, 0
	v_mov_b32_e32 v219, 0
	v_mov_b32_e32 v220, 0
	v_mov_b32_e32 v221, 0
	v_mov_b32_e32 v222, 0
	v_mov_b32_e32 v223, 0
	v_mov_b32_e32 v224, 0
	v_mov_b32_e32 v225, 0
	v_mov_b32_e32 v242, 0
	v_mov_b32_e32 v243, 0
	v_mov_b32_e32 v244, 0
	v_mov_b32_e32 v245, 0
	v_mov_b32_e32 v246, 0
	v_mov_b32_e32 v247, 0
	v_mov_b32_e32 v248, 0
	v_mov_b32_e32 v249, 0
	v_mov_b32_e32 v132, 0
	v_mov_b32_e32 v133, 0
	v_mov_b32_e32 v134, 0
	v_mov_b32_e32 v135, 0
	v_mov_b32_e32 v136, 0
	v_mov_b32_e32 v137, 0
	v_mov_b32_e32 v138, 0
	v_mov_b32_e32 v139, 0
	v_mov_b32_e32 v148, 0
	v_mov_b32_e32 v149, 0
	v_mov_b32_e32 v150, 0
	v_mov_b32_e32 v151, 0
	v_mov_b32_e32 v152, 0
	v_mov_b32_e32 v153, 0
	v_mov_b32_e32 v154, 0
	v_mov_b32_e32 v155, 0
	s_mov_b32 s56, 0
	s_nop 7
	s_nop 4
	s_cmp_lg_u32 s64, 0
	s_cbranch_scc1 .Lmla_p_nomask
	v_sub_u32_e32 v0, v188, v208
	s_nop 0
	v_cmp_le_i32_e32 vcc, 0, v0
	v_cmp_le_i32_e64 s[6:7], 1, v0
	s_nop 0
	v_cndmask_b32_e32 v64, v204, v64, vcc
	v_cndmask_b32_e64 v65, v204, v65, s[6:7]
	v_cmp_le_i32_e32 vcc, 2, v0
	v_cmp_le_i32_e64 s[6:7], 3, v0
	s_nop 0
	v_cndmask_b32_e32 v66, v204, v66, vcc
	v_cndmask_b32_e64 v67, v204, v67, s[6:7]
	v_cmp_le_i32_e32 vcc, 8, v0
	v_cmp_le_i32_e64 s[6:7], 9, v0
	s_nop 0
	v_cndmask_b32_e32 v68, v204, v68, vcc
	v_cndmask_b32_e64 v69, v204, v69, s[6:7]
	v_cmp_le_i32_e32 vcc, 10, v0
	v_cmp_le_i32_e64 s[6:7], 11, v0
	s_nop 0
	v_cndmask_b32_e32 v70, v204, v70, vcc
	v_cndmask_b32_e64 v71, v204, v71, s[6:7]
	v_cmp_le_i32_e32 vcc, 16, v0
	v_cmp_le_i32_e64 s[6:7], 17, v0
	s_nop 0
	v_cndmask_b32_e32 v72, v204, v72, vcc
	v_cndmask_b32_e64 v73, v204, v73, s[6:7]
	v_cmp_le_i32_e32 vcc, 18, v0
	v_cmp_le_i32_e64 s[6:7], 19, v0
	s_nop 0
	v_cndmask_b32_e32 v74, v204, v74, vcc
	v_cndmask_b32_e64 v75, v204, v75, s[6:7]
	v_cmp_le_i32_e32 vcc, 24, v0
	v_cmp_le_i32_e64 s[6:7], 25, v0
	s_nop 0
	v_cndmask_b32_e32 v76, v204, v76, vcc
	v_cndmask_b32_e64 v77, v204, v77, s[6:7]
	v_cmp_le_i32_e32 vcc, 26, v0
	v_cmp_le_i32_e64 s[6:7], 27, v0
	s_nop 0
	v_cndmask_b32_e32 v78, v204, v78, vcc
	v_cndmask_b32_e64 v79, v204, v79, s[6:7]
	v_cmp_le_i32_e32 vcc, 32, v0
	v_cmp_le_i32_e64 s[6:7], 33, v0
	s_nop 0
	v_cndmask_b32_e32 v80, v204, v80, vcc
	v_cndmask_b32_e64 v81, v204, v81, s[6:7]
	v_cmp_le_i32_e32 vcc, 34, v0
	v_cmp_le_i32_e64 s[6:7], 35, v0
	s_nop 0
	v_cndmask_b32_e32 v82, v204, v82, vcc
	v_cndmask_b32_e64 v83, v204, v83, s[6:7]
	v_cmp_le_i32_e32 vcc, 40, v0
	v_cmp_le_i32_e64 s[6:7], 41, v0
	s_nop 0
	v_cndmask_b32_e32 v84, v204, v84, vcc
	v_cndmask_b32_e64 v85, v204, v85, s[6:7]
	v_cmp_le_i32_e32 vcc, 42, v0
	v_cmp_le_i32_e64 s[6:7], 43, v0
	s_nop 0
	v_cndmask_b32_e32 v86, v204, v86, vcc
	v_cndmask_b32_e64 v87, v204, v87, s[6:7]
	v_cmp_le_i32_e32 vcc, 48, v0
	v_cmp_le_i32_e64 s[6:7], 49, v0
	s_nop 0
	v_cndmask_b32_e32 v88, v204, v88, vcc
	v_cndmask_b32_e64 v89, v204, v89, s[6:7]
	v_cmp_le_i32_e32 vcc, 50, v0
	v_cmp_le_i32_e64 s[6:7], 51, v0
	s_nop 0
	v_cndmask_b32_e32 v90, v204, v90, vcc
	v_cndmask_b32_e64 v91, v204, v91, s[6:7]
	v_cmp_le_i32_e32 vcc, 56, v0
	v_cmp_le_i32_e64 s[6:7], 57, v0
	s_nop 0
	v_cndmask_b32_e32 v92, v204, v92, vcc
	v_cndmask_b32_e64 v93, v204, v93, s[6:7]
	v_cmp_le_i32_e32 vcc, 58, v0
	v_cmp_le_i32_e64 s[6:7], 59, v0
	s_nop 0
	v_cndmask_b32_e32 v94, v204, v94, vcc
	v_cndmask_b32_e64 v95, v204, v95, s[6:7]

.Lmla_loop:
.Lmla_it0:
	s_cmp_ge_u32 s65, s45
	s_cbranch_scc1 .Lmla_skip0
	ds_read_b128 v[164:167], v210 offset:25600
	ds_read_b128 v[168:171], v210 offset:25632
	ds_read_b128 v[172:175], v210 offset:25664
	ds_read_b128 v[214:217], v210 offset:25696
	s_add_i32 s42, s65, 3
	s_min_u32 s42, s42, s44
	s_lshl_b64 s[6:7], s[42:43], 17
	v_lshl_add_u64 v[14:15], v[190:191], 0, s[6:7]
	s_lshl_b64 s[6:7], s[42:43], 12
	v_lshl_add_u64 v[200:201], v[194:195], 0, s[6:7]
	s_add_i32 s42, s65, 2
	s_min_u32 s42, s42, s44
	s_lshl_b64 s[6:7], s[42:43], 17
	v_lshl_add_u64 v[252:253], v[192:193], 0, s[6:7]
	global_load_dwordx4 v[6:9], v[14:15], off
	global_load_dwordx4 v[10:13], v[252:253], off
	global_load_dwordx4 v[2:5], v[200:201], off
	s_cmp_ge_u32 s65, s64
	s_cbranch_scc1 .Lmla_mask0
.Lmla_maskret0:
	v_max3_f32 v251, v64, v65, v66
	v_max3_f32 v251, v251, v67, v68
	v_max3_f32 v251, v251, v69, v70
	v_max3_f32 v251, v251, v71, v72
	v_max3_f32 v251, v251, v73, v74
	v_mfma_f32_32x32x16_bf16 v[32:47], v[226:229], v[132:135], v[32:47]
	ds_read_b64_tr_b16 v[226:227], v211 offset:13312
	ds_read_b64_tr_b16 v[228:229], v211 offset:14848
	v_max3_f32 v251, v251, v75, v76
	v_max3_f32 v251, v251, v77, v78
	v_max_f32_e32 v251, v251, v79
	v_max3_f32 v252, v80, v81, v82
	v_mfma_f32_32x32x16_bf16 v[16:31], v[230:233], v[132:135], v[16:31]
	ds_read_b64_tr_b16 v[230:231], v211 offset:13376
	ds_read_b64_tr_b16 v[232:233], v211 offset:14912
	v_max3_f32 v252, v252, v83, v84
	v_max3_f32 v252, v252, v85, v86
	v_max3_f32 v252, v252, v87, v88
	v_max3_f32 v252, v252, v89, v90
	v_mfma_f32_32x32x16_bf16 v[32:47], v[234:237], v[136:139], v[32:47]
	ds_read_b64_tr_b16 v[234:235], v211 offset:16384
	ds_read_b64_tr_b16 v[236:237], v211 offset:17920
	v_max3_f32 v252, v252, v91, v92
	v_max3_f32 v252, v252, v93, v94
	v_max_f32_e32 v252, v252, v95
	v_max_f32_e32 v251, v251, v252
	v_mfma_f32_32x32x16_bf16 v[16:31], v[238:241], v[136:139], v[16:31]
	ds_read_b64_tr_b16 v[238:239], v211 offset:16448
	ds_read_b64_tr_b16 v[240:241], v211 offset:17984
	v_mov_b32_e32 v252, v251
	s_nop 1
	v_permlane32_swap_b32_e32 v251, v252
	v_max_f32_e32 v251, v251, v252
	v_cmp_lt_f32_e32 vcc, 0x41000000, v251
	s_cbranch_vccnz .Lmla_rare0
.Lmla_rareret0:
	v_mfma_f32_32x32x16_bf16 v[32:47], v[218:221], v[148:151], v[32:47]
	ds_read_b64_tr_b16 v[218:219], v211 offset:19456
	s_waitcnt lgkmcnt(9)
	ds_read_b64_tr_b16 v[220:221], v211 offset:20992
	v_exp_f32_e32 v64, v64
	v_exp_f32_e32 v65, v65
	v_exp_f32_e32 v66, v66
	v_exp_f32_e32 v67, v67
	v_mfma_f32_32x32x16_bf16 v[16:31], v[222:225], v[148:151], v[16:31]
	ds_read_b64_tr_b16 v[222:223], v211 offset:19520
	ds_read_b64_tr_b16 v[224:225], v211 offset:21056
	v_add_f32_e32 v15, v64, v65
	v_add_f32_e32 v213, v66, v67
	v_add_f32_e32 v14, v15, v213
	v_exp_f32_e32 v68, v68
	v_exp_f32_e32 v69, v69
	v_mfma_f32_32x32x16_bf16 v[32:47], v[242:245], v[152:155], v[32:47]
	ds_read_b64_tr_b16 v[242:243], v211 offset:22528
	s_waitcnt lgkmcnt(9)
	ds_read_b64_tr_b16 v[244:245], v211 offset:24064
	v_exp_f32_e32 v70, v70
	v_exp_f32_e32 v71, v71
	v_add_f32_e32 v15, v68, v69
	v_add_f32_e32 v213, v70, v71
	v_mfma_f32_32x32x16_bf16 v[16:31], v[246:249], v[152:155], v[16:31]
	ds_read_b64_tr_b16 v[246:247], v211 offset:22592
	ds_read_b64_tr_b16 v[248:249], v211 offset:24128
	v_add_f32_e32 v15, v15, v213
	v_add_f32_e32 v14, v14, v15
	v_cvt_pk_bf16_f32 v64, v64, v65
	v_cvt_pk_bf16_f32 v65, v66, v67
	v_cvt_pk_bf16_f32 v66, v68, v69
	v_cvt_pk_bf16_f32 v67, v70, v71
	v_exp_f32_e32 v72, v72
	s_cmp_lg_u32 s56, 0
	s_cbranch_scc1 .Lmla_fix0
.Lmla_fixret0:
	v_mfma_f32_32x32x16_bf16 v[132:147], v[164:167], v[96:99], v[48:63]
	ds_read_b128 v[164:167], v210 offset:25728
	v_exp_f32_e32 v73, v73
	v_exp_f32_e32 v74, v74
	v_exp_f32_e32 v75, v75
	v_mfma_f32_32x32x16_bf16 v[132:147], v[168:171], v[100:103], v[132:147]
	s_waitcnt lgkmcnt(9)
	ds_read_b128 v[168:171], v210 offset:25760
	v_add_f32_e32 v15, v72, v73
	v_add_f32_e32 v213, v74, v75
	v_add_f32_e32 v15, v15, v213
	v_add_f32_e32 v14, v14, v15
	v_exp_f32_e32 v76, v76
	v_exp_f32_e32 v77, v77
	v_mfma_f32_32x32x16_bf16 v[132:147], v[172:175], v[104:107], v[132:147]
	ds_read_b128 v[172:175], v210 offset:32256
	v_exp_f32_e32 v78, v78
	v_exp_f32_e32 v79, v79
	v_add_f32_e32 v15, v76, v77
	v_add_f32_e32 v213, v78, v79
	v_mfma_f32_32x32x16_bf16 v[132:147], v[214:217], v[108:111], v[132:147]
	ds_read_b128 v[214:217], v210 offset:32288
	v_add_f32_e32 v15, v15, v213
	v_add_f32_e32 v14, v14, v15
	v_cvt_pk_bf16_f32 v68, v72, v73
	v_cvt_pk_bf16_f32 v69, v74, v75
	v_cvt_pk_bf16_f32 v70, v76, v77
	v_cvt_pk_bf16_f32 v71, v78, v79
	v_exp_f32_e32 v80, v80
	s_waitcnt lgkmcnt(3)
	v_mfma_f32_32x32x16_bf16 v[132:147], v[164:167], v[112:115], v[132:147]
	ds_read_b128 v[164:167], v210 offset:32320
	v_exp_f32_e32 v81, v81
	v_exp_f32_e32 v82, v82
	v_exp_f32_e32 v83, v83
	s_waitcnt lgkmcnt(3)
	v_mfma_f32_32x32x16_bf16 v[132:147], v[168:171], v[116:119], v[132:147]
	ds_read_b128 v[168:171], v210 offset:32352
	v_add_f32_e32 v15, v80, v81
	v_add_f32_e32 v213, v82, v83
	v_add_f32_e32 v15, v15, v213
	v_add_f32_e32 v14, v14, v15
	v_exp_f32_e32 v84, v84
	v_exp_f32_e32 v85, v85
	s_waitcnt lgkmcnt(3)
	v_mfma_f32_32x32x16_bf16 v[148:163], v[172:175], v[96:99], v[48:63]
	ds_read_b128 v[172:175], v210 offset:32384
	v_exp_f32_e32 v86, v86
	v_exp_f32_e32 v87, v87
	v_add_f32_e32 v15, v84, v85
	v_add_f32_e32 v213, v86, v87
	s_waitcnt lgkmcnt(3)
	v_mfma_f32_32x32x16_bf16 v[148:163], v[214:217], v[100:103], v[148:163]
	ds_read_b128 v[214:217], v210 offset:32416
	v_add_f32_e32 v15, v15, v213
	v_add_f32_e32 v14, v14, v15
	v_cvt_pk_bf16_f32 v80, v80, v81
	v_cvt_pk_bf16_f32 v81, v82, v83
	v_cvt_pk_bf16_f32 v82, v84, v85
	v_cvt_pk_bf16_f32 v83, v86, v87
	v_exp_f32_e32 v88, v88
	s_waitcnt lgkmcnt(3)
	v_mfma_f32_32x32x16_bf16 v[148:163], v[164:167], v[104:107], v[148:163]
	s_waitcnt vmcnt(3)
	ds_write_b128 v205, v[120:123] offset:0
	ds_write_b128 v206, v[124:127] offset:38912
	ds_write_b128 v207, v[128:131] offset:128
	v_exp_f32_e32 v89, v89
	v_exp_f32_e32 v90, v90
	v_exp_f32_e32 v91, v91
	s_waitcnt lgkmcnt(5)
	v_mfma_f32_32x32x16_bf16 v[148:163], v[168:171], v[108:111], v[148:163]
	v_add_f32_e32 v15, v88, v89
	v_add_f32_e32 v213, v90, v91
	v_add_f32_e32 v15, v15, v213
	v_add_f32_e32 v14, v14, v15
	v_exp_f32_e32 v92, v92
	v_exp_f32_e32 v93, v93
	s_waitcnt lgkmcnt(4)
	v_mfma_f32_32x32x16_bf16 v[148:163], v[172:175], v[112:115], v[148:163]
	v_exp_f32_e32 v94, v94
	v_exp_f32_e32 v95, v95
	v_add_f32_e32 v15, v92, v93
	v_add_f32_e32 v213, v94, v95
	s_waitcnt lgkmcnt(3)
	v_mfma_f32_32x32x16_bf16 v[148:163], v[214:217], v[116:119], v[148:163]
	v_add_f32_e32 v15, v15, v213
	v_add_f32_e32 v14, v14, v15
	v_cvt_pk_bf16_f32 v84, v88, v89
	v_cvt_pk_bf16_f32 v85, v90, v91
	v_cvt_pk_bf16_f32 v86, v92, v93
	v_cvt_pk_bf16_f32 v87, v94, v95
	v_add_f32_e32 v209, v209, v14
	s_waitcnt lgkmcnt(0)
	s_barrier
.Lmla_end0:
.Lmla_it1:
	s_add_i32 s66, s65, 1
	s_cmp_ge_u32 s66, s45
	s_cbranch_scc1 .Lmla_skip1
	ds_read_b128 v[164:167], v210 offset:0
	ds_read_b128 v[168:171], v210 offset:32
	ds_read_b128 v[172:175], v210 offset:64
	ds_read_b128 v[214:217], v210 offset:96
	s_add_i32 s42, s66, 3
	s_min_u32 s42, s42, s44
	s_lshl_b64 s[6:7], s[42:43], 17
	v_lshl_add_u64 v[14:15], v[190:191], 0, s[6:7]
	s_lshl_b64 s[6:7], s[42:43], 12
	v_lshl_add_u64 v[200:201], v[194:195], 0, s[6:7]
	s_add_i32 s42, s66, 2
	s_min_u32 s42, s42, s44
	s_lshl_b64 s[6:7], s[42:43], 17
	v_lshl_add_u64 v[252:253], v[192:193], 0, s[6:7]
	global_load_dwordx4 v[120:123], v[14:15], off
	global_load_dwordx4 v[124:127], v[252:253], off
	global_load_dwordx4 v[128:131], v[200:201], off
	s_cmp_ge_u32 s66, s64
	s_cbranch_scc1 .Lmla_mask1
.Lmla_maskret1:
	v_max3_f32 v251, v132, v133, v134
	v_max3_f32 v251, v251, v135, v136
	v_max3_f32 v251, v251, v137, v138
	v_max3_f32 v251, v251, v139, v140
	v_max3_f32 v251, v251, v141, v142
	v_mfma_f32_32x32x16_bf16 v[32:47], v[226:229], v[64:67], v[32:47]
	ds_read_b64_tr_b16 v[226:227], v211 offset:38912
	ds_read_b64_tr_b16 v[228:229], v211 offset:40448
	v_max3_f32 v251, v251, v143, v144
	v_max3_f32 v251, v251, v145, v146
	v_max_f32_e32 v251, v251, v147
	v_max3_f32 v252, v148, v149, v150
	v_mfma_f32_32x32x16_bf16 v[16:31], v[230:233], v[64:67], v[16:31]
	ds_read_b64_tr_b16 v[230:231], v211 offset:38976
	ds_read_b64_tr_b16 v[232:233], v211 offset:40512
	v_max3_f32 v252, v252, v151, v152
	v_max3_f32 v252, v252, v153, v154
	v_max3_f32 v252, v252, v155, v156
	v_max3_f32 v252, v252, v157, v158
	v_mfma_f32_32x32x16_bf16 v[32:47], v[234:237], v[68:71], v[32:47]
	ds_read_b64_tr_b16 v[234:235], v211 offset:41984
	ds_read_b64_tr_b16 v[236:237], v211 offset:43520
	v_max3_f32 v252, v252, v159, v160
	v_max3_f32 v252, v252, v161, v162
	v_max_f32_e32 v252, v252, v163
	v_max_f32_e32 v251, v251, v252
	v_mfma_f32_32x32x16_bf16 v[16:31], v[238:241], v[68:71], v[16:31]
	ds_read_b64_tr_b16 v[238:239], v211 offset:42048
	ds_read_b64_tr_b16 v[240:241], v211 offset:43584
	v_mov_b32_e32 v252, v251
	s_nop 1
	v_permlane32_swap_b32_e32 v251, v252
	v_max_f32_e32 v251, v251, v252
	v_cmp_lt_f32_e32 vcc, 0x41000000, v251
	s_cbranch_vccnz .Lmla_rare1
.Lmla_rareret1:
	v_mfma_f32_32x32x16_bf16 v[32:47], v[218:221], v[80:83], v[32:47]
	ds_read_b64_tr_b16 v[218:219], v211 offset:45056
	s_waitcnt lgkmcnt(9)
	ds_read_b64_tr_b16 v[220:221], v211 offset:46592
	v_exp_f32_e32 v132, v132
	v_exp_f32_e32 v133, v133
	v_exp_f32_e32 v134, v134
	v_exp_f32_e32 v135, v135
	v_mfma_f32_32x32x16_bf16 v[16:31], v[222:225], v[80:83], v[16:31]
	ds_read_b64_tr_b16 v[222:223], v211 offset:45120
	ds_read_b64_tr_b16 v[224:225], v211 offset:46656
	v_add_f32_e32 v15, v132, v133
	v_add_f32_e32 v213, v134, v135
	v_add_f32_e32 v14, v15, v213
	v_exp_f32_e32 v136, v136
	v_exp_f32_e32 v137, v137
	v_mfma_f32_32x32x16_bf16 v[32:47], v[242:245], v[84:87], v[32:47]
	ds_read_b64_tr_b16 v[242:243], v211 offset:48128
	s_waitcnt lgkmcnt(9)
	ds_read_b64_tr_b16 v[244:245], v211 offset:49664
	v_exp_f32_e32 v138, v138
	v_exp_f32_e32 v139, v139
	v_add_f32_e32 v15, v136, v137
	v_add_f32_e32 v213, v138, v139
	v_mfma_f32_32x32x16_bf16 v[16:31], v[246:249], v[84:87], v[16:31]
	ds_read_b64_tr_b16 v[246:247], v211 offset:48192
	ds_read_b64_tr_b16 v[248:249], v211 offset:49728
	v_add_f32_e32 v15, v15, v213
	v_add_f32_e32 v14, v14, v15
	v_cvt_pk_bf16_f32 v132, v132, v133
	v_cvt_pk_bf16_f32 v133, v134, v135
	v_cvt_pk_bf16_f32 v134, v136, v137
	v_cvt_pk_bf16_f32 v135, v138, v139
	v_exp_f32_e32 v140, v140
	s_cmp_lg_u32 s56, 0
	s_cbranch_scc1 .Lmla_fix1
; __device__ __forceinline__ void mla_unit(int h, int qb, const bf16_t* __restrict__ Qm, const bf16_t* __restrict__ Km, const bf16_t* __restrict__ Kr, const bf16_t* __restrict__ Vm, bf16_t* ZM, LAS char* lds) {
;     ...
;     for (int t = 0; t < NT; t += 2) {
;         MLA_STEP(t, gknA, gvA, gkrA, gknB, gvB, gkrB);
;         MLA_STEP(t + 1, gknB, gvB, gkrB, gknA, gvA, gkrA);
;     }
.Lmla_fixret1:
	v_mfma_f32_32x32x16_bf16 v[64:79], v[164:167], v[96:99], v[48:63]
	ds_read_b128 v[164:167], v210 offset:128
	v_exp_f32_e32 v141, v141
	v_exp_f32_e32 v142, v142
	v_exp_f32_e32 v143, v143
	v_mfma_f32_32x32x16_bf16 v[64:79], v[168:171], v[100:103], v[64:79]
	s_waitcnt lgkmcnt(9)
	ds_read_b128 v[168:171], v210 offset:160
	v_add_f32_e32 v15, v140, v141
	v_add_f32_e32 v213, v142, v143
	v_add_f32_e32 v15, v15, v213
	v_add_f32_e32 v14, v14, v15
	v_exp_f32_e32 v144, v144
	v_exp_f32_e32 v145, v145
	v_mfma_f32_32x32x16_bf16 v[64:79], v[172:175], v[104:107], v[64:79]
	ds_read_b128 v[172:175], v210 offset:6656
	v_exp_f32_e32 v146, v146
	v_exp_f32_e32 v147, v147
	v_add_f32_e32 v15, v144, v145
	v_add_f32_e32 v213, v146, v147
	v_mfma_f32_32x32x16_bf16 v[64:79], v[214:217], v[108:111], v[64:79]
	ds_read_b128 v[214:217], v210 offset:6688
	v_add_f32_e32 v15, v15, v213
	v_add_f32_e32 v14, v14, v15
	v_cvt_pk_bf16_f32 v136, v140, v141
	v_cvt_pk_bf16_f32 v137, v142, v143
	v_cvt_pk_bf16_f32 v138, v144, v145
	v_cvt_pk_bf16_f32 v139, v146, v147
	v_exp_f32_e32 v148, v148
	s_waitcnt lgkmcnt(3)
	v_mfma_f32_32x32x16_bf16 v[64:79], v[164:167], v[112:115], v[64:79]
	ds_read_b128 v[164:167], v210 offset:6720
	v_exp_f32_e32 v149, v149
	v_exp_f32_e32 v150, v150
	v_exp_f32_e32 v151, v151
	s_waitcnt lgkmcnt(3)
	v_mfma_f32_32x32x16_bf16 v[64:79], v[168:171], v[116:119], v[64:79]
	ds_read_b128 v[168:171], v210 offset:6752
	v_add_f32_e32 v15, v148, v149
	v_add_f32_e32 v213, v150, v151
	v_add_f32_e32 v15, v15, v213
	v_add_f32_e32 v14, v14, v15
	v_exp_f32_e32 v152, v152
	v_exp_f32_e32 v153, v153
	s_waitcnt lgkmcnt(3)
	v_mfma_f32_32x32x16_bf16 v[80:95], v[172:175], v[96:99], v[48:63]
	ds_read_b128 v[172:175], v210 offset:6784
	v_exp_f32_e32 v154, v154
	v_exp_f32_e32 v155, v155
	v_add_f32_e32 v15, v152, v153
	v_add_f32_e32 v213, v154, v155
	s_waitcnt lgkmcnt(3)
	v_mfma_f32_32x32x16_bf16 v[80:95], v[214:217], v[100:103], v[80:95]
	ds_read_b128 v[214:217], v210 offset:6816
	v_add_f32_e32 v15, v15, v213
	v_add_f32_e32 v14, v14, v15
	v_cvt_pk_bf16_f32 v148, v148, v149
	v_cvt_pk_bf16_f32 v149, v150, v151
	v_cvt_pk_bf16_f32 v150, v152, v153
	v_cvt_pk_bf16_f32 v151, v154, v155
	v_exp_f32_e32 v156, v156
	s_waitcnt lgkmcnt(3)
	v_mfma_f32_32x32x16_bf16 v[80:95], v[164:167], v[104:107], v[80:95]
	s_waitcnt vmcnt(3)
	ds_write_b128 v205, v[6:9] offset:25600
	ds_write_b128 v206, v[10:13] offset:13312
	ds_write_b128 v207, v[2:5] offset:25728
	v_exp_f32_e32 v157, v157
	v_exp_f32_e32 v158, v158
	v_exp_f32_e32 v159, v159
	s_waitcnt lgkmcnt(5)
	v_mfma_f32_32x32x16_bf16 v[80:95], v[168:171], v[108:111], v[80:95]
	v_add_f32_e32 v15, v156, v157
	v_add_f32_e32 v213, v158, v159
	v_add_f32_e32 v15, v15, v213
	v_add_f32_e32 v14, v14, v15
	v_exp_f32_e32 v160, v160
	v_exp_f32_e32 v161, v161
	s_waitcnt lgkmcnt(4)
	v_mfma_f32_32x32x16_bf16 v[80:95], v[172:175], v[112:115], v[80:95]
	v_exp_f32_e32 v162, v162
	v_exp_f32_e32 v163, v163
	v_add_f32_e32 v15, v160, v161
	v_add_f32_e32 v213, v162, v163
	s_waitcnt lgkmcnt(3)
	v_mfma_f32_32x32x16_bf16 v[80:95], v[214:217], v[116:119], v[80:95]
	v_add_f32_e32 v15, v15, v213
	v_add_f32_e32 v14, v14, v15
	v_cvt_pk_bf16_f32 v152, v156, v157
	v_cvt_pk_bf16_f32 v153, v158, v159
	v_cvt_pk_bf16_f32 v154, v160, v161
	v_cvt_pk_bf16_f32 v155, v162, v163
	v_add_f32_e32 v209, v209, v14
	s_waitcnt lgkmcnt(0)
	s_barrier
.Lmla_end1:
	s_add_i32 s65, s65, 2
	s_cmp_lt_u32 s65, s40
	s_cbranch_scc1 .Lmla_loop
	s_cmp_lg_u32 s45, s40
	s_cbranch_scc1 .Lmla_done
	v_mfma_f32_32x32x16_bf16 v[32:47], v[226:229], v[132:135], v[32:47]
	v_mfma_f32_32x32x16_bf16 v[16:31], v[230:233], v[132:135], v[16:31]
	v_mfma_f32_32x32x16_bf16 v[32:47], v[234:237], v[136:139], v[32:47]
	v_mfma_f32_32x32x16_bf16 v[16:31], v[238:241], v[136:139], v[16:31]
	v_mfma_f32_32x32x16_bf16 v[32:47], v[218:221], v[148:151], v[32:47]
	v_mfma_f32_32x32x16_bf16 v[16:31], v[222:225], v[148:151], v[16:31]
	v_mfma_f32_32x32x16_bf16 v[32:47], v[242:245], v[152:155], v[32:47]
	v_mfma_f32_32x32x16_bf16 v[16:31], v[246:249], v[152:155], v[16:31]
	s_nop 7
.Lmla_done:
	s_waitcnt vmcnt(3)
	s_branch .LBB0_741
.Lmla_skip0:
	s_add_i32 s42, s65, 3
	s_min_u32 s42, s42, s44
	s_lshl_b64 s[6:7], s[42:43], 17
	v_lshl_add_u64 v[14:15], v[190:191], 0, s[6:7]
	s_lshl_b64 s[6:7], s[42:43], 12
	v_lshl_add_u64 v[200:201], v[194:195], 0, s[6:7]
	s_add_i32 s42, s65, 2
	s_min_u32 s42, s42, s44
	s_lshl_b64 s[6:7], s[42:43], 17
	v_lshl_add_u64 v[252:253], v[192:193], 0, s[6:7]
	global_load_dwordx4 v[6:9], v[14:15], off
	global_load_dwordx4 v[10:13], v[252:253], off
	global_load_dwordx4 v[2:5], v[200:201], off
	s_cmp_lg_u32 s65, s45
	s_cbranch_scc1 .Lmla_skipb0
	v_mfma_f32_32x32x16_bf16 v[32:47], v[226:229], v[132:135], v[32:47]
	v_mfma_f32_32x32x16_bf16 v[16:31], v[230:233], v[132:135], v[16:31]
	v_mfma_f32_32x32x16_bf16 v[32:47], v[234:237], v[136:139], v[32:47]
	v_mfma_f32_32x32x16_bf16 v[16:31], v[238:241], v[136:139], v[16:31]
	v_mfma_f32_32x32x16_bf16 v[32:47], v[218:221], v[148:151], v[32:47]
	v_mfma_f32_32x32x16_bf16 v[16:31], v[222:225], v[148:151], v[16:31]
	v_mfma_f32_32x32x16_bf16 v[32:47], v[242:245], v[152:155], v[32:47]
	v_mfma_f32_32x32x16_bf16 v[16:31], v[246:249], v[152:155], v[16:31]

.Lmla_mask0:
	s_lshl_b32 s27, s65, 6
	v_sub_u32_e32 v0, v188, v208
	v_subrev_u32_e32 v0, s27, v0
	s_nop 0
	v_cmp_le_i32_e32 vcc, 0, v0
	v_cmp_le_i32_e64 s[6:7], 1, v0
	s_nop 0
	v_cndmask_b32_e32 v64, v204, v64, vcc
	v_cndmask_b32_e64 v65, v204, v65, s[6:7]
	v_cmp_le_i32_e32 vcc, 2, v0
	v_cmp_le_i32_e64 s[6:7], 3, v0
	s_nop 0
	v_cndmask_b32_e32 v66, v204, v66, vcc
	v_cndmask_b32_e64 v67, v204, v67, s[6:7]
	v_cmp_le_i32_e32 vcc, 8, v0
	v_cmp_le_i32_e64 s[6:7], 9, v0
	s_nop 0
	v_cndmask_b32_e32 v68, v204, v68, vcc
	v_cndmask_b32_e64 v69, v204, v69, s[6:7]
	v_cmp_le_i32_e32 vcc, 10, v0
	v_cmp_le_i32_e64 s[6:7], 11, v0
	s_nop 0
	v_cndmask_b32_e32 v70, v204, v70, vcc
	v_cndmask_b32_e64 v71, v204, v71, s[6:7]
	v_cmp_le_i32_e32 vcc, 16, v0
	v_cmp_le_i32_e64 s[6:7], 17, v0
	s_nop 0
	v_cndmask_b32_e32 v72, v204, v72, vcc
	v_cndmask_b32_e64 v73, v204, v73, s[6:7]
	v_cmp_le_i32_e32 vcc, 18, v0
	v_cmp_le_i32_e64 s[6:7], 19, v0
	s_nop 0
	v_cndmask_b32_e32 v74, v204, v74, vcc
	v_cndmask_b32_e64 v75, v204, v75, s[6:7]
	v_cmp_le_i32_e32 vcc, 24, v0
	v_cmp_le_i32_e64 s[6:7], 25, v0
	s_nop 0
	v_cndmask_b32_e32 v76, v204, v76, vcc
	v_cndmask_b32_e64 v77, v204, v77, s[6:7]
	v_cmp_le_i32_e32 vcc, 26, v0
	v_cmp_le_i32_e64 s[6:7], 27, v0
	s_nop 0
	v_cndmask_b32_e32 v78, v204, v78, vcc
	v_cndmask_b32_e64 v79, v204, v79, s[6:7]
	v_cmp_le_i32_e32 vcc, 32, v0
	v_cmp_le_i32_e64 s[6:7], 33, v0
	s_nop 0
	v_cndmask_b32_e32 v80, v204, v80, vcc
	v_cndmask_b32_e64 v81, v204, v81, s[6:7]
	v_cmp_le_i32_e32 vcc, 34, v0
	v_cmp_le_i32_e64 s[6:7], 35, v0
	s_nop 0
	v_cndmask_b32_e32 v82, v204, v82, vcc
	v_cndmask_b32_e64 v83, v204, v83, s[6:7]
	v_cmp_le_i32_e32 vcc, 40, v0
	v_cmp_le_i32_e64 s[6:7], 41, v0
	s_nop 0
	v_cndmask_b32_e32 v84, v204, v84, vcc
	v_cndmask_b32_e64 v85, v204, v85, s[6:7]
	v_cmp_le_i32_e32 vcc, 42, v0
	v_cmp_le_i32_e64 s[6:7], 43, v0
	s_nop 0
	v_cndmask_b32_e32 v86, v204, v86, vcc
	v_cndmask_b32_e64 v87, v204, v87, s[6:7]
	v_cmp_le_i32_e32 vcc, 48, v0
	v_cmp_le_i32_e64 s[6:7], 49, v0
	s_nop 0
	v_cndmask_b32_e32 v88, v204, v88, vcc
	v_cndmask_b32_e64 v89, v204, v89, s[6:7]
	v_cmp_le_i32_e32 vcc, 50, v0
	v_cmp_le_i32_e64 s[6:7], 51, v0
	s_nop 0
	v_cndmask_b32_e32 v90, v204, v90, vcc
	v_cndmask_b32_e64 v91, v204, v91, s[6:7]
	v_cmp_le_i32_e32 vcc, 56, v0
	v_cmp_le_i32_e64 s[6:7], 57, v0
	s_nop 0
	v_cndmask_b32_e32 v92, v204, v92, vcc
	v_cndmask_b32_e64 v93, v204, v93, s[6:7]
	v_cmp_le_i32_e32 vcc, 58, v0
	v_cmp_le_i32_e64 s[6:7], 59, v0
	s_nop 0
	v_cndmask_b32_e32 v94, v204, v94, vcc
	v_cndmask_b32_e64 v95, v204, v95, s[6:7]
	s_branch .Lmla_maskret0
.Lmla_rare0:
	v_max_f32_e32 v253, 0, v251
	v_add_f32_e32 v212, v212, v253
	v_exp_f32_e64 v250, -v253
	v_xor_b32_e32 v48, 0x80000000, v212
	v_sub_f32_e32 v64, v64, v253
	v_sub_f32_e32 v65, v65, v253
	v_sub_f32_e32 v66, v66, v253
	v_sub_f32_e32 v67, v67, v253
	v_sub_f32_e32 v68, v68, v253
	v_sub_f32_e32 v69, v69, v253
	v_sub_f32_e32 v70, v70, v253
	v_sub_f32_e32 v71, v71, v253
	v_sub_f32_e32 v72, v72, v253
	v_sub_f32_e32 v73, v73, v253
	v_sub_f32_e32 v74, v74, v253
	v_sub_f32_e32 v75, v75, v253
	v_sub_f32_e32 v76, v76, v253
	v_sub_f32_e32 v77, v77, v253
	v_sub_f32_e32 v78, v78, v253
	v_sub_f32_e32 v79, v79, v253
	v_sub_f32_e32 v80, v80, v253
	v_sub_f32_e32 v81, v81, v253
	v_sub_f32_e32 v82, v82, v253
	v_sub_f32_e32 v83, v83, v253
	v_sub_f32_e32 v84, v84, v253
	v_sub_f32_e32 v85, v85, v253
	v_sub_f32_e32 v86, v86, v253
	v_sub_f32_e32 v87, v87, v253
	v_sub_f32_e32 v88, v88, v253
	v_sub_f32_e32 v89, v89, v253
	v_sub_f32_e32 v90, v90, v253
	v_sub_f32_e32 v91, v91, v253
	v_sub_f32_e32 v92, v92, v253
	v_sub_f32_e32 v93, v93, v253
	v_sub_f32_e32 v94, v94, v253
	v_sub_f32_e32 v95, v95, v253
	v_mov_b32_e32 v49, v48
	v_mov_b32_e32 v50, v48
	v_mov_b32_e32 v51, v48
	v_mov_b32_e32 v52, v48
	v_mov_b32_e32 v53, v48
	v_mov_b32_e32 v54, v48
	v_mov_b32_e32 v55, v48
	v_mov_b32_e32 v56, v48
	v_mov_b32_e32 v57, v48
	v_mov_b32_e32 v58, v48
	v_mov_b32_e32 v59, v48
	v_mov_b32_e32 v60, v48
	v_mov_b32_e32 v61, v48
	v_mov_b32_e32 v62, v48
	v_mov_b32_e32 v63, v48
	v_mul_f32_e32 v209, v209, v250
	s_mov_b32 s56, 1
	s_branch .Lmla_rareret0
.Lmla_fix0:
	s_nop 7
	s_nop 4
	v_mul_f32_e32 v32, v32, v250
	v_mul_f32_e32 v33, v33, v250
	v_mul_f32_e32 v34, v34, v250
	v_mul_f32_e32 v35, v35, v250
	v_mul_f32_e32 v36, v36, v250
	v_mul_f32_e32 v37, v37, v250
	v_mul_f32_e32 v38, v38, v250
	v_mul_f32_e32 v39, v39, v250
	v_mul_f32_e32 v40, v40, v250
	v_mul_f32_e32 v41, v41, v250
	v_mul_f32_e32 v42, v42, v250
	v_mul_f32_e32 v43, v43, v250
	v_mul_f32_e32 v44, v44, v250
	v_mul_f32_e32 v45, v45, v250
	v_mul_f32_e32 v46, v46, v250
	v_mul_f32_e32 v47, v47, v250
	v_mul_f32_e32 v16, v16, v250
	v_mul_f32_e32 v17, v17, v250
	v_mul_f32_e32 v18, v18, v250
	v_mul_f32_e32 v19, v19, v250
	v_mul_f32_e32 v20, v20, v250
	v_mul_f32_e32 v21, v21, v250
	v_mul_f32_e32 v22, v22, v250
	v_mul_f32_e32 v23, v23, v250
	v_mul_f32_e32 v24, v24, v250
	v_mul_f32_e32 v25, v25, v250
	v_mul_f32_e32 v26, v26, v250
	v_mul_f32_e32 v27, v27, v250
	v_mul_f32_e32 v28, v28, v250
	v_mul_f32_e32 v29, v29, v250
	v_mul_f32_e32 v30, v30, v250
	v_mul_f32_e32 v31, v31, v250
	s_mov_b32 s56, 0
	s_branch .Lmla_fixret0
.Lmla_skip1:
	s_add_i32 s42, s66, 3
	s_min_u32 s42, s42, s44
	s_lshl_b64 s[6:7], s[42:43], 17
	v_lshl_add_u64 v[14:15], v[190:191], 0, s[6:7]
	s_lshl_b64 s[6:7], s[42:43], 12
	v_lshl_add_u64 v[200:201], v[194:195], 0, s[6:7]
	s_add_i32 s42, s66, 2
	s_min_u32 s42, s42, s44
	s_lshl_b64 s[6:7], s[42:43], 17
	v_lshl_add_u64 v[252:253], v[192:193], 0, s[6:7]
	global_load_dwordx4 v[120:123], v[14:15], off
	global_load_dwordx4 v[124:127], v[252:253], off
	global_load_dwordx4 v[128:131], v[200:201], off
	s_cmp_lg_u32 s66, s45
	s_cbranch_scc1 .Lmla_skipb1
	v_mfma_f32_32x32x16_bf16 v[32:47], v[226:229], v[64:67], v[32:47]
	v_mfma_f32_32x32x16_bf16 v[16:31], v[230:233], v[64:67], v[16:31]
	v_mfma_f32_32x32x16_bf16 v[32:47], v[234:237], v[68:71], v[32:47]
	v_mfma_f32_32x32x16_bf16 v[16:31], v[238:241], v[68:71], v[16:31]
	v_mfma_f32_32x32x16_bf16 v[32:47], v[218:221], v[80:83], v[32:47]
	v_mfma_f32_32x32x16_bf16 v[16:31], v[222:225], v[80:83], v[16:31]
	v_mfma_f32_32x32x16_bf16 v[32:47], v[242:245], v[84:87], v[32:47]
	v_mfma_f32_32x32x16_bf16 v[16:31], v[246:249], v[84:87], v[16:31]

.Lmla_mask1:
	s_lshl_b32 s27, s66, 6
	v_sub_u32_e32 v0, v188, v208
	v_subrev_u32_e32 v0, s27, v0
	s_nop 0
	v_cmp_le_i32_e32 vcc, 0, v0
	v_cmp_le_i32_e64 s[6:7], 1, v0
	s_nop 0
	v_cndmask_b32_e32 v132, v204, v132, vcc
	v_cndmask_b32_e64 v133, v204, v133, s[6:7]
	v_cmp_le_i32_e32 vcc, 2, v0
	v_cmp_le_i32_e64 s[6:7], 3, v0
	s_nop 0
	v_cndmask_b32_e32 v134, v204, v134, vcc
	v_cndmask_b32_e64 v135, v204, v135, s[6:7]
	v_cmp_le_i32_e32 vcc, 8, v0
	v_cmp_le_i32_e64 s[6:7], 9, v0
	s_nop 0
	v_cndmask_b32_e32 v136, v204, v136, vcc
	v_cndmask_b32_e64 v137, v204, v137, s[6:7]
	v_cmp_le_i32_e32 vcc, 10, v0
	v_cmp_le_i32_e64 s[6:7], 11, v0
	s_nop 0
	v_cndmask_b32_e32 v138, v204, v138, vcc
	v_cndmask_b32_e64 v139, v204, v139, s[6:7]
	v_cmp_le_i32_e32 vcc, 16, v0
	v_cmp_le_i32_e64 s[6:7], 17, v0
	s_nop 0
	v_cndmask_b32_e32 v140, v204, v140, vcc
	v_cndmask_b32_e64 v141, v204, v141, s[6:7]
	v_cmp_le_i32_e32 vcc, 18, v0
	v_cmp_le_i32_e64 s[6:7], 19, v0
	s_nop 0
	v_cndmask_b32_e32 v142, v204, v142, vcc
	v_cndmask_b32_e64 v143, v204, v143, s[6:7]
	v_cmp_le_i32_e32 vcc, 24, v0
	v_cmp_le_i32_e64 s[6:7], 25, v0
	s_nop 0
	v_cndmask_b32_e32 v144, v204, v144, vcc
	v_cndmask_b32_e64 v145, v204, v145, s[6:7]
	v_cmp_le_i32_e32 vcc, 26, v0
	v_cmp_le_i32_e64 s[6:7], 27, v0
	s_nop 0
	v_cndmask_b32_e32 v146, v204, v146, vcc
	v_cndmask_b32_e64 v147, v204, v147, s[6:7]
	v_cmp_le_i32_e32 vcc, 32, v0
	v_cmp_le_i32_e64 s[6:7], 33, v0
	s_nop 0
	v_cndmask_b32_e32 v148, v204, v148, vcc
	v_cndmask_b32_e64 v149, v204, v149, s[6:7]
	v_cmp_le_i32_e32 vcc, 34, v0
	v_cmp_le_i32_e64 s[6:7], 35, v0
	s_nop 0
	v_cndmask_b32_e32 v150, v204, v150, vcc
	v_cndmask_b32_e64 v151, v204, v151, s[6:7]
	v_cmp_le_i32_e32 vcc, 40, v0
	v_cmp_le_i32_e64 s[6:7], 41, v0
	s_nop 0
	v_cndmask_b32_e32 v152, v204, v152, vcc
	v_cndmask_b32_e64 v153, v204, v153, s[6:7]
	v_cmp_le_i32_e32 vcc, 42, v0
	v_cmp_le_i32_e64 s[6:7], 43, v0
	s_nop 0
	v_cndmask_b32_e32 v154, v204, v154, vcc
	v_cndmask_b32_e64 v155, v204, v155, s[6:7]
	v_cmp_le_i32_e32 vcc, 48, v0
	v_cmp_le_i32_e64 s[6:7], 49, v0
	s_nop 0
	v_cndmask_b32_e32 v156, v204, v156, vcc
	v_cndmask_b32_e64 v157, v204, v157, s[6:7]
	v_cmp_le_i32_e32 vcc, 50, v0
	v_cmp_le_i32_e64 s[6:7], 51, v0
	s_nop 0
	v_cndmask_b32_e32 v158, v204, v158, vcc
	v_cndmask_b32_e64 v159, v204, v159, s[6:7]
	v_cmp_le_i32_e32 vcc, 56, v0
	v_cmp_le_i32_e64 s[6:7], 57, v0
	s_nop 0
	v_cndmask_b32_e32 v160, v204, v160, vcc
	v_cndmask_b32_e64 v161, v204, v161, s[6:7]
	v_cmp_le_i32_e32 vcc, 58, v0
	v_cmp_le_i32_e64 s[6:7], 59, v0
	s_nop 0
	v_cndmask_b32_e32 v162, v204, v162, vcc
	v_cndmask_b32_e64 v163, v204, v163, s[6:7]
	s_branch .Lmla_maskret1
.Lmla_rare1:
	v_max_f32_e32 v253, 0, v251
	v_add_f32_e32 v212, v212, v253
	v_exp_f32_e64 v250, -v253
	v_xor_b32_e32 v48, 0x80000000, v212
	v_sub_f32_e32 v132, v132, v253
	v_sub_f32_e32 v133, v133, v253
	v_sub_f32_e32 v134, v134, v253
	v_sub_f32_e32 v135, v135, v253
	v_sub_f32_e32 v136, v136, v253
	v_sub_f32_e32 v137, v137, v253
	v_sub_f32_e32 v138, v138, v253
	v_sub_f32_e32 v139, v139, v253
	v_sub_f32_e32 v140, v140, v253
	v_sub_f32_e32 v141, v141, v253
	v_sub_f32_e32 v142, v142, v253
	v_sub_f32_e32 v143, v143, v253
	v_sub_f32_e32 v144, v144, v253
	v_sub_f32_e32 v145, v145, v253
	v_sub_f32_e32 v146, v146, v253
	v_sub_f32_e32 v147, v147, v253
	v_sub_f32_e32 v148, v148, v253
	v_sub_f32_e32 v149, v149, v253
	v_sub_f32_e32 v150, v150, v253
	v_sub_f32_e32 v151, v151, v253
	v_sub_f32_e32 v152, v152, v253
	v_sub_f32_e32 v153, v153, v253
	v_sub_f32_e32 v154, v154, v253
	v_sub_f32_e32 v155, v155, v253
	v_sub_f32_e32 v156, v156, v253
	v_sub_f32_e32 v157, v157, v253
	v_sub_f32_e32 v158, v158, v253
	v_sub_f32_e32 v159, v159, v253
	v_sub_f32_e32 v160, v160, v253
	v_sub_f32_e32 v161, v161, v253
	v_sub_f32_e32 v162, v162, v253
	v_sub_f32_e32 v163, v163, v253
	v_mov_b32_e32 v49, v48
	v_mov_b32_e32 v50, v48
	v_mov_b32_e32 v51, v48
	v_mov_b32_e32 v52, v48
	v_mov_b32_e32 v53, v48
	v_mov_b32_e32 v54, v48
	v_mov_b32_e32 v55, v48
	v_mov_b32_e32 v56, v48
	v_mov_b32_e32 v57, v48
	v_mov_b32_e32 v58, v48
	v_mov_b32_e32 v59, v48
	v_mov_b32_e32 v60, v48
	v_mov_b32_e32 v61, v48
	v_mov_b32_e32 v62, v48
	v_mov_b32_e32 v63, v48
	v_mul_f32_e32 v209, v209, v250
	s_mov_b32 s56, 1
	s_branch .Lmla_rareret1
